# attention stash layout lane-interleaved within the wave's own region: each stash store/reload instruction covers 1 KB of whole cache lines instead of 64 separate 16-byte pieces
# speedup vs baseline: 1.0117x; 1.0117x over previous
.Lat_nolast_11:
	s_waitcnt vmcnt(0) lgkmcnt(0)
	s_barrier
	ds_bpermute_b32 v182, v214, v81
	s_waitcnt lgkmcnt(0)
	v_add_f32_e32 v64, v81, v182
	v_div_scale_f32 v65, s[36:37], v64, v64, 1.0
	v_rcp_f32_e32 v66, v65
	v_div_scale_f32 v67, vcc, 1.0, v64, 1.0
	v_fma_f32 v68, -v65, v66, 1.0
	v_fmac_f32_e32 v66, v68, v66
	v_mul_f32_e32 v68, v67, v66
	v_fma_f32 v69, -v65, v68, v67
	v_fmac_f32_e32 v68, v69, v66
	v_fma_f32 v65, -v65, v68, v67
	v_div_fmas_f32 v65, v65, v66, v68
	v_div_fixup_f32 v72, v65, v64, 1.0
	v_mul_f32_e32 v0, v0, v72
	v_mul_f32_e32 v1, v1, v72
	v_mul_f32_e32 v2, v2, v72
	v_mul_f32_e32 v3, v3, v72
	v_mul_f32_e32 v4, v4, v72
	v_mul_f32_e32 v5, v5, v72
	v_mul_f32_e32 v6, v6, v72
	v_mul_f32_e32 v7, v7, v72
	v_mul_f32_e32 v8, v8, v72
	v_mul_f32_e32 v9, v9, v72
	v_mul_f32_e32 v10, v10, v72
	v_mul_f32_e32 v11, v11, v72
	v_mul_f32_e32 v12, v12, v72
	v_mul_f32_e32 v13, v13, v72
	v_mul_f32_e32 v14, v14, v72
	v_mul_f32_e32 v15, v15, v72
	v_mul_f32_e32 v16, v16, v72
	v_mul_f32_e32 v17, v17, v72
	v_mul_f32_e32 v18, v18, v72
	v_mul_f32_e32 v19, v19, v72
	v_mul_f32_e32 v20, v20, v72
	v_mul_f32_e32 v21, v21, v72
	v_mul_f32_e32 v22, v22, v72
	v_mul_f32_e32 v23, v23, v72
	v_mul_f32_e32 v24, v24, v72
	v_mul_f32_e32 v25, v25, v72
	v_mul_f32_e32 v26, v26, v72
	v_mul_f32_e32 v27, v27, v72
	v_mul_f32_e32 v28, v28, v72
	v_mul_f32_e32 v29, v29, v72
	v_mul_f32_e32 v30, v30, v72
	v_mul_f32_e32 v31, v31, v72
	v_mul_f32_e32 v32, v32, v72
	v_mul_f32_e32 v33, v33, v72
	v_mul_f32_e32 v34, v34, v72
	v_mul_f32_e32 v35, v35, v72
	v_mul_f32_e32 v36, v36, v72
	v_mul_f32_e32 v37, v37, v72
	v_mul_f32_e32 v38, v38, v72
	v_mul_f32_e32 v39, v39, v72
	v_mul_f32_e32 v40, v40, v72
	v_mul_f32_e32 v41, v41, v72
	v_mul_f32_e32 v42, v42, v72
	v_mul_f32_e32 v43, v43, v72
	v_mul_f32_e32 v44, v44, v72
	v_mul_f32_e32 v45, v45, v72
	v_mul_f32_e32 v46, v46, v72
	v_mul_f32_e32 v47, v47, v72
	v_mul_f32_e32 v48, v48, v72
	v_mul_f32_e32 v49, v49, v72
	v_mul_f32_e32 v50, v50, v72
	v_mul_f32_e32 v51, v51, v72
	v_mul_f32_e32 v52, v52, v72
	v_mul_f32_e32 v53, v53, v72
	v_mul_f32_e32 v54, v54, v72
	v_mul_f32_e32 v55, v55, v72
	v_mul_f32_e32 v56, v56, v72
	v_mul_f32_e32 v57, v57, v72
	v_mul_f32_e32 v58, v58, v72
	v_mul_f32_e32 v59, v59, v72
	v_mul_f32_e32 v60, v60, v72
	v_mul_f32_e32 v61, v61, v72
	v_mul_f32_e32 v62, v62, v72
	v_mul_f32_e32 v63, v63, v72
	s_cmp_lg_u32 s7, 0
	s_cbranch_scc1 .Lat_combine
	v_and_b32_e32 v82, 63, v195
	v_mul_u32_u24_e32 v82, 0xf0, v82
	v_sub_u32_e32 v82, 0, v82
	v_ashrrev_i32_e32 v83, 31, v82
	s_movk_i32 s8, 0x1000
	s_mov_b32 s9, 0
	v_lshl_add_u64 v[82:83], v[170:171], 0, v[82:83]
	v_lshl_add_u64 v[84:85], v[82:83], 0, s[8:9]
	v_lshl_add_u64 v[86:87], v[84:85], 0, s[8:9]
	v_lshl_add_u64 v[88:89], v[86:87], 0, s[8:9]
	global_store_dwordx4 v[82:83], v[0:3], off
	global_store_dwordx4 v[82:83], v[4:7], off offset:1024
	global_store_dwordx4 v[82:83], v[8:11], off offset:2048
	global_store_dwordx4 v[82:83], v[12:15], off offset:3072
	global_store_dwordx4 v[84:85], v[16:19], off
	global_store_dwordx4 v[84:85], v[20:23], off offset:1024
	global_store_dwordx4 v[84:85], v[24:27], off offset:2048
	global_store_dwordx4 v[84:85], v[28:31], off offset:3072
	global_store_dwordx4 v[86:87], v[32:35], off
	global_store_dwordx4 v[86:87], v[36:39], off offset:1024
	global_store_dwordx4 v[86:87], v[40:43], off offset:2048
	global_store_dwordx4 v[86:87], v[44:47], off offset:3072
	global_store_dwordx4 v[88:89], v[48:51], off
	global_store_dwordx4 v[88:89], v[52:55], off offset:1024
	global_store_dwordx4 v[88:89], v[56:59], off offset:2048
	global_store_dwordx4 v[88:89], v[60:63], off offset:3072
	s_mov_b32 s7, 1
	s_branch .Lat_stream
.Lat_combine:
	v_and_b32_e32 v64, 63, v195
	v_mul_u32_u24_e32 v64, 0xf0, v64
	v_sub_u32_e32 v64, 0, v64
	v_ashrrev_i32_e32 v65, 31, v64
	s_movk_i32 s8, 0x1000
	s_mov_b32 s9, 0
	v_lshl_add_u64 v[64:65], v[170:171], 0, v[64:65]
	v_lshl_add_u64 v[66:67], v[64:65], 0, s[8:9]
	v_lshl_add_u64 v[68:69], v[66:67], 0, s[8:9]
	v_lshl_add_u64 v[70:71], v[68:69], 0, s[8:9]
	global_load_dwordx4 v[82:85], v[64:65], off
	global_load_dwordx4 v[86:89], v[64:65], off offset:1024
	global_load_dwordx4 v[90:93], v[64:65], off offset:2048
	global_load_dwordx4 v[94:97], v[64:65], off offset:3072
	global_load_dwordx4 v[98:101], v[66:67], off
	global_load_dwordx4 v[102:105], v[66:67], off offset:1024
	global_load_dwordx4 v[106:109], v[66:67], off offset:2048
	global_load_dwordx4 v[110:113], v[66:67], off offset:3072
	global_load_dwordx4 v[114:117], v[68:69], off
	global_load_dwordx4 v[118:121], v[68:69], off offset:1024
	global_load_dwordx4 v[122:125], v[68:69], off offset:2048
	global_load_dwordx4 v[126:129], v[68:69], off offset:3072
	global_load_dwordx4 v[130:133], v[70:71], off
	global_load_dwordx4 v[134:137], v[70:71], off offset:1024
	global_load_dwordx4 v[138:141], v[70:71], off offset:2048
	global_load_dwordx4 v[142:145], v[70:71], off offset:3072
	v_mov_b32_e32 v181, 0
	s_waitcnt vmcnt(15)
	v_fma_f32 v82, -v190, v0, v82
	v_fma_f32 v83, -v190, v1, v83
	v_fma_f32 v84, -v190, v2, v84
	v_fma_f32 v85, -v190, v3, v85
	v_fmac_f32_e32 v181, v82, v82
	v_fmac_f32_e32 v181, v83, v83
	v_fmac_f32_e32 v181, v84, v84
	v_fmac_f32_e32 v181, v85, v85
	global_load_dwordx4 v[0:3], v[172:173], off
	s_waitcnt vmcnt(15)
	v_fma_f32 v86, -v190, v4, v86
	v_fma_f32 v87, -v190, v5, v87
	v_fma_f32 v88, -v190, v6, v88
	v_fma_f32 v89, -v190, v7, v89
	v_fmac_f32_e32 v181, v86, v86
	v_fmac_f32_e32 v181, v87, v87
	v_fmac_f32_e32 v181, v88, v88
	v_fmac_f32_e32 v181, v89, v89
	global_load_dwordx4 v[4:7], v[172:173], off offset:32
	s_waitcnt vmcnt(15)
	v_fma_f32 v90, -v190, v8, v90
	v_fma_f32 v91, -v190, v9, v91
	v_fma_f32 v92, -v190, v10, v92
	v_fma_f32 v93, -v190, v11, v93
	v_fmac_f32_e32 v181, v90, v90
	v_fmac_f32_e32 v181, v91, v91
	v_fmac_f32_e32 v181, v92, v92
	v_fmac_f32_e32 v181, v93, v93
	global_load_dwordx4 v[8:11], v[172:173], off offset:64
	s_waitcnt vmcnt(15)
	v_fma_f32 v94, -v190, v12, v94
	v_fma_f32 v95, -v190, v13, v95
	v_fma_f32 v96, -v190, v14, v96
	v_fma_f32 v97, -v190, v15, v97
	v_fmac_f32_e32 v181, v94, v94
	v_fmac_f32_e32 v181, v95, v95
	v_fmac_f32_e32 v181, v96, v96
	v_fmac_f32_e32 v181, v97, v97
	global_load_dwordx4 v[12:15], v[172:173], off offset:96
	s_waitcnt vmcnt(15)
	v_fma_f32 v98, -v190, v16, v98
	v_fma_f32 v99, -v190, v17, v99
	v_fma_f32 v100, -v190, v18, v100
	v_fma_f32 v101, -v190, v19, v101
	v_fmac_f32_e32 v181, v98, v98
	v_fmac_f32_e32 v181, v99, v99
	v_fmac_f32_e32 v181, v100, v100
	v_fmac_f32_e32 v181, v101, v101
	global_load_dwordx4 v[16:19], v[172:173], off offset:128
	s_waitcnt vmcnt(15)
	v_fma_f32 v102, -v190, v20, v102
	v_fma_f32 v103, -v190, v21, v103
	v_fma_f32 v104, -v190, v22, v104
	v_fma_f32 v105, -v190, v23, v105
	v_fmac_f32_e32 v181, v102, v102
	v_fmac_f32_e32 v181, v103, v103
	v_fmac_f32_e32 v181, v104, v104
	v_fmac_f32_e32 v181, v105, v105
	global_load_dwordx4 v[20:23], v[172:173], off offset:160
	s_waitcnt vmcnt(15)
	v_fma_f32 v106, -v190, v24, v106
	v_fma_f32 v107, -v190, v25, v107
	v_fma_f32 v108, -v190, v26, v108
	v_fma_f32 v109, -v190, v27, v109
	v_fmac_f32_e32 v181, v106, v106
	v_fmac_f32_e32 v181, v107, v107
	v_fmac_f32_e32 v181, v108, v108
	v_fmac_f32_e32 v181, v109, v109
	global_load_dwordx4 v[24:27], v[172:173], off offset:192
	s_waitcnt vmcnt(15)
	v_fma_f32 v110, -v190, v28, v110
	v_fma_f32 v111, -v190, v29, v111
	v_fma_f32 v112, -v190, v30, v112
	v_fma_f32 v113, -v190, v31, v113
	v_fmac_f32_e32 v181, v110, v110
	v_fmac_f32_e32 v181, v111, v111
	v_fmac_f32_e32 v181, v112, v112
	v_fmac_f32_e32 v181, v113, v113
	global_load_dwordx4 v[28:31], v[172:173], off offset:224
	s_waitcnt vmcnt(15)
	v_fma_f32 v114, -v190, v32, v114
	v_fma_f32 v115, -v190, v33, v115
	v_fma_f32 v116, -v190, v34, v116
	v_fma_f32 v117, -v190, v35, v117
	v_fmac_f32_e32 v181, v114, v114
	v_fmac_f32_e32 v181, v115, v115
	v_fmac_f32_e32 v181, v116, v116
	v_fmac_f32_e32 v181, v117, v117
	global_load_dwordx4 v[32:35], v[172:173], off offset:256
	s_waitcnt vmcnt(15)
	v_fma_f32 v118, -v190, v36, v118
	v_fma_f32 v119, -v190, v37, v119
	v_fma_f32 v120, -v190, v38, v120
	v_fma_f32 v121, -v190, v39, v121
	v_fmac_f32_e32 v181, v118, v118
	v_fmac_f32_e32 v181, v119, v119
	v_fmac_f32_e32 v181, v120, v120
	v_fmac_f32_e32 v181, v121, v121
	global_load_dwordx4 v[36:39], v[172:173], off offset:288
	s_waitcnt vmcnt(15)
	v_fma_f32 v122, -v190, v40, v122
	v_fma_f32 v123, -v190, v41, v123
	v_fma_f32 v124, -v190, v42, v124
	v_fma_f32 v125, -v190, v43, v125
	v_fmac_f32_e32 v181, v122, v122
	v_fmac_f32_e32 v181, v123, v123
	v_fmac_f32_e32 v181, v124, v124
	v_fmac_f32_e32 v181, v125, v125
	global_load_dwordx4 v[40:43], v[172:173], off offset:320
	s_waitcnt vmcnt(15)
	v_fma_f32 v126, -v190, v44, v126
	v_fma_f32 v127, -v190, v45, v127
	v_fma_f32 v128, -v190, v46, v128
	v_fma_f32 v129, -v190, v47, v129
	v_fmac_f32_e32 v181, v126, v126
	v_fmac_f32_e32 v181, v127, v127
	v_fmac_f32_e32 v181, v128, v128
	v_fmac_f32_e32 v181, v129, v129
	global_load_dwordx4 v[44:47], v[172:173], off offset:352
	s_waitcnt vmcnt(15)
	v_fma_f32 v130, -v190, v48, v130
	v_fma_f32 v131, -v190, v49, v131
	v_fma_f32 v132, -v190, v50, v132
	v_fma_f32 v133, -v190, v51, v133
	v_fmac_f32_e32 v181, v130, v130
	v_fmac_f32_e32 v181, v131, v131
	v_fmac_f32_e32 v181, v132, v132
	v_fmac_f32_e32 v181, v133, v133
	global_load_dwordx4 v[48:51], v[172:173], off offset:384
	s_waitcnt vmcnt(15)
	v_fma_f32 v134, -v190, v52, v134
	v_fma_f32 v135, -v190, v53, v135
	v_fma_f32 v136, -v190, v54, v136
	v_fma_f32 v137, -v190, v55, v137
	v_fmac_f32_e32 v181, v134, v134
	v_fmac_f32_e32 v181, v135, v135
	v_fmac_f32_e32 v181, v136, v136
	v_fmac_f32_e32 v181, v137, v137
	global_load_dwordx4 v[52:55], v[172:173], off offset:416
	s_waitcnt vmcnt(15)
	v_fma_f32 v138, -v190, v56, v138
	v_fma_f32 v139, -v190, v57, v139
	v_fma_f32 v140, -v190, v58, v140
	v_fma_f32 v141, -v190, v59, v141
	v_fmac_f32_e32 v181, v138, v138
	v_fmac_f32_e32 v181, v139, v139
	v_fmac_f32_e32 v181, v140, v140
	v_fmac_f32_e32 v181, v141, v141
	global_load_dwordx4 v[56:59], v[172:173], off offset:448
	s_waitcnt vmcnt(15)
	v_fma_f32 v142, -v190, v60, v142
	v_fma_f32 v143, -v190, v61, v143
	v_fma_f32 v144, -v190, v62, v144
	v_fma_f32 v145, -v190, v63, v145
	v_fmac_f32_e32 v181, v142, v142
	v_fmac_f32_e32 v181, v143, v143
	v_fmac_f32_e32 v181, v144, v144
	v_fmac_f32_e32 v181, v145, v145
	global_load_dwordx4 v[60:63], v[172:173], off offset:480
	ds_bpermute_b32 v182, v214, v181
	s_waitcnt lgkmcnt(0)
	v_add_f32_e32 v181, v181, v182
	v_fmamk_f32 v181, v181, 0x3c000000, v194
	v_rsq_f32_e32 v181, v181
	s_nop 0
	v_mul_f32_e32 v181, v191, v181
	v_and_b32_e32 v64, 32, v195
	v_lshrrev_b32_e32 v64, 2, v64
	v_mov_b32_e32 v65, 0
	v_lshl_add_u64 v[66:67], v[174:175], 0, v[64:65]
	s_waitcnt vmcnt(14)
	v_mul_f32_e32 v82, v82, v181
	v_mul_f32_e32 v83, v83, v181
	v_mul_f32_e32 v84, v84, v181
	v_mul_f32_e32 v85, v85, v181
	v_mul_f32_e32 v82, v0, v82
	v_mul_f32_e32 v83, v1, v83
	v_mul_f32_e32 v84, v2, v84
	v_mul_f32_e32 v85, v3, v85
	v_mul_f32_e32 v86, v86, v181
	v_mul_f32_e32 v87, v87, v181
	v_mul_f32_e32 v88, v88, v181
	v_mul_f32_e32 v89, v89, v181
	v_mul_f32_e32 v86, v4, v86
	v_mul_f32_e32 v87, v5, v87
	v_mul_f32_e32 v88, v6, v88
	v_mul_f32_e32 v89, v7, v89
	v_cvt_pk_bf16_f32 v82, v82, v83
	v_cvt_pk_bf16_f32 v83, v84, v85
	v_cvt_pk_bf16_f32 v84, v86, v87
	v_cvt_pk_bf16_f32 v85, v88, v89
	s_nop 1
	v_permlane32_swap_b32_e32 v82, v84
	v_permlane32_swap_b32_e32 v83, v85
	global_store_dwordx4 v[66:67], v[82:85], off
	s_waitcnt vmcnt(13)
	v_mul_f32_e32 v90, v90, v181
	v_mul_f32_e32 v91, v91, v181
	v_mul_f32_e32 v92, v92, v181
	v_mul_f32_e32 v93, v93, v181
	v_mul_f32_e32 v90, v8, v90
	v_mul_f32_e32 v91, v9, v91
	v_mul_f32_e32 v92, v10, v92
	v_mul_f32_e32 v93, v11, v93
	v_mul_f32_e32 v94, v94, v181
	v_mul_f32_e32 v95, v95, v181
	v_mul_f32_e32 v96, v96, v181
	v_mul_f32_e32 v97, v97, v181
	v_mul_f32_e32 v94, v12, v94
	v_mul_f32_e32 v95, v13, v95
	v_mul_f32_e32 v96, v14, v96
	v_mul_f32_e32 v97, v15, v97
	v_cvt_pk_bf16_f32 v90, v90, v91
	v_cvt_pk_bf16_f32 v91, v92, v93
	v_cvt_pk_bf16_f32 v92, v94, v95
	v_cvt_pk_bf16_f32 v93, v96, v97
	s_nop 1
	v_permlane32_swap_b32_e32 v90, v92
	v_permlane32_swap_b32_e32 v91, v93
	global_store_dwordx4 v[66:67], v[90:93], off offset:32
	s_waitcnt vmcnt(12)
	v_mul_f32_e32 v98, v98, v181
	v_mul_f32_e32 v99, v99, v181
	v_mul_f32_e32 v100, v100, v181
	v_mul_f32_e32 v101, v101, v181
	v_mul_f32_e32 v98, v16, v98
	v_mul_f32_e32 v99, v17, v99
	v_mul_f32_e32 v100, v18, v100
	v_mul_f32_e32 v101, v19, v101
	v_mul_f32_e32 v102, v102, v181
	v_mul_f32_e32 v103, v103, v181
	v_mul_f32_e32 v104, v104, v181
	v_mul_f32_e32 v105, v105, v181
	v_mul_f32_e32 v102, v20, v102
	v_mul_f32_e32 v103, v21, v103
	v_mul_f32_e32 v104, v22, v104
	v_mul_f32_e32 v105, v23, v105
	v_cvt_pk_bf16_f32 v98, v98, v99
	v_cvt_pk_bf16_f32 v99, v100, v101
	v_cvt_pk_bf16_f32 v100, v102, v103
	v_cvt_pk_bf16_f32 v101, v104, v105
	s_nop 1
	v_permlane32_swap_b32_e32 v98, v100
	v_permlane32_swap_b32_e32 v99, v101
	global_store_dwordx4 v[66:67], v[98:101], off offset:64
	s_waitcnt vmcnt(11)
	v_mul_f32_e32 v106, v106, v181
	v_mul_f32_e32 v107, v107, v181
	v_mul_f32_e32 v108, v108, v181
	v_mul_f32_e32 v109, v109, v181
	v_mul_f32_e32 v106, v24, v106
	v_mul_f32_e32 v107, v25, v107
	v_mul_f32_e32 v108, v26, v108
	v_mul_f32_e32 v109, v27, v109
	v_mul_f32_e32 v110, v110, v181
	v_mul_f32_e32 v111, v111, v181
	v_mul_f32_e32 v112, v112, v181
	v_mul_f32_e32 v113, v113, v181
	v_mul_f32_e32 v110, v28, v110
	v_mul_f32_e32 v111, v29, v111
	v_mul_f32_e32 v112, v30, v112
	v_mul_f32_e32 v113, v31, v113
	v_cvt_pk_bf16_f32 v106, v106, v107
	v_cvt_pk_bf16_f32 v107, v108, v109
	v_cvt_pk_bf16_f32 v108, v110, v111
	v_cvt_pk_bf16_f32 v109, v112, v113
	s_nop 1
	v_permlane32_swap_b32_e32 v106, v108
	v_permlane32_swap_b32_e32 v107, v109
	global_store_dwordx4 v[66:67], v[106:109], off offset:96
	s_waitcnt vmcnt(10)
	v_mul_f32_e32 v114, v114, v181
	v_mul_f32_e32 v115, v115, v181
	v_mul_f32_e32 v116, v116, v181
	v_mul_f32_e32 v117, v117, v181
	v_mul_f32_e32 v114, v32, v114
	v_mul_f32_e32 v115, v33, v115
	v_mul_f32_e32 v116, v34, v116
	v_mul_f32_e32 v117, v35, v117
	v_mul_f32_e32 v118, v118, v181
	v_mul_f32_e32 v119, v119, v181
	v_mul_f32_e32 v120, v120, v181
	v_mul_f32_e32 v121, v121, v181
	v_mul_f32_e32 v118, v36, v118
	v_mul_f32_e32 v119, v37, v119
	v_mul_f32_e32 v120, v38, v120
	v_mul_f32_e32 v121, v39, v121
	v_cvt_pk_bf16_f32 v114, v114, v115
	v_cvt_pk_bf16_f32 v115, v116, v117
	v_cvt_pk_bf16_f32 v116, v118, v119
	v_cvt_pk_bf16_f32 v117, v120, v121
	s_nop 1
	v_permlane32_swap_b32_e32 v114, v116
	v_permlane32_swap_b32_e32 v115, v117
	global_store_dwordx4 v[66:67], v[114:117], off offset:128
	s_waitcnt vmcnt(9)
	v_mul_f32_e32 v122, v122, v181
	v_mul_f32_e32 v123, v123, v181
	v_mul_f32_e32 v124, v124, v181
	v_mul_f32_e32 v125, v125, v181
	v_mul_f32_e32 v122, v40, v122
	v_mul_f32_e32 v123, v41, v123
	v_mul_f32_e32 v124, v42, v124
	v_mul_f32_e32 v125, v43, v125
	v_mul_f32_e32 v126, v126, v181
	v_mul_f32_e32 v127, v127, v181
	v_mul_f32_e32 v128, v128, v181
	v_mul_f32_e32 v129, v129, v181
	v_mul_f32_e32 v126, v44, v126
	v_mul_f32_e32 v127, v45, v127
	v_mul_f32_e32 v128, v46, v128
	v_mul_f32_e32 v129, v47, v129
	v_cvt_pk_bf16_f32 v122, v122, v123
	v_cvt_pk_bf16_f32 v123, v124, v125
	v_cvt_pk_bf16_f32 v124, v126, v127
	v_cvt_pk_bf16_f32 v125, v128, v129
	s_nop 1
	v_permlane32_swap_b32_e32 v122, v124
	v_permlane32_swap_b32_e32 v123, v125
	global_store_dwordx4 v[66:67], v[122:125], off offset:160
	s_waitcnt vmcnt(8)
	v_mul_f32_e32 v130, v130, v181
	v_mul_f32_e32 v131, v131, v181
	v_mul_f32_e32 v132, v132, v181
	v_mul_f32_e32 v133, v133, v181
	v_mul_f32_e32 v130, v48, v130
	v_mul_f32_e32 v131, v49, v131
	v_mul_f32_e32 v132, v50, v132
	v_mul_f32_e32 v133, v51, v133
	v_mul_f32_e32 v134, v134, v181
	v_mul_f32_e32 v135, v135, v181
	v_mul_f32_e32 v136, v136, v181
	v_mul_f32_e32 v137, v137, v181
	v_mul_f32_e32 v134, v52, v134
	v_mul_f32_e32 v135, v53, v135
	v_mul_f32_e32 v136, v54, v136
	v_mul_f32_e32 v137, v55, v137
	v_cvt_pk_bf16_f32 v130, v130, v131
	v_cvt_pk_bf16_f32 v131, v132, v133
	v_cvt_pk_bf16_f32 v132, v134, v135
	v_cvt_pk_bf16_f32 v133, v136, v137
	s_nop 1
	v_permlane32_swap_b32_e32 v130, v132
	v_permlane32_swap_b32_e32 v131, v133
	global_store_dwordx4 v[66:67], v[130:133], off offset:192
	s_waitcnt vmcnt(7)
	v_mul_f32_e32 v138, v138, v181
	v_mul_f32_e32 v139, v139, v181
	v_mul_f32_e32 v140, v140, v181
	v_mul_f32_e32 v141, v141, v181
	v_mul_f32_e32 v138, v56, v138
	v_mul_f32_e32 v139, v57, v139
	v_mul_f32_e32 v140, v58, v140
	v_mul_f32_e32 v141, v59, v141
	v_mul_f32_e32 v142, v142, v181
	v_mul_f32_e32 v143, v143, v181
	v_mul_f32_e32 v144, v144, v181
	v_mul_f32_e32 v145, v145, v181
	v_mul_f32_e32 v142, v60, v142
	v_mul_f32_e32 v143, v61, v143
	v_mul_f32_e32 v144, v62, v144
	v_mul_f32_e32 v145, v63, v145
	v_cvt_pk_bf16_f32 v138, v138, v139
	v_cvt_pk_bf16_f32 v139, v140, v141
	v_cvt_pk_bf16_f32 v140, v142, v143
	v_cvt_pk_bf16_f32 v141, v144, v145
	s_nop 1
	v_permlane32_swap_b32_e32 v138, v140
	v_permlane32_swap_b32_e32 v139, v141
	global_store_dwordx4 v[66:67], v[138:141], off offset:224
	s_branch .LBB0_231
